# speedup vs baseline: 1.0093x; 1.0093x over previous
; template <int EPI>
; __device__ __forceinline__ void gemm_phase(const Params& p, const u16* __restrict__ A, const u16* __restrict__ Bt, int K, int nN,
;                            u16* __restrict__ Cout, int ldc) {
;     ...
;       GSTEP(0, 2); GSTEP(1, 6); GSTEP(2, 6); GSTEP(3, 6); GSTEP(4, 2); GSTEP(5, 2); GSTEP(6, 2); GSTEP(7, 2);
;       GSTEP(8, 2); GSTEP(9, 2); GSTEP(10, 2); GSTEP(11, 2); GSTEP(12, 2); GSTEP(13, 2); GSTEP(14, 1); GSTEP(15, 0);
.Lwi_head:
	s_waitcnt lgkmcnt(2)
	s_setprio 1
	v_mfma_f32_16x16x32_bf16 v[124:127], v[228:231], v[212:215], v[124:127]
	v_mfma_f32_16x16x32_bf16 v[120:123], v[228:231], v[216:219], v[120:123]
	v_mfma_f32_16x16x32_bf16 v[116:119], v[228:231], v[220:223], v[116:119]
	v_mfma_f32_16x16x32_bf16 v[112:115], v[228:231], v[224:227], v[112:115]
	s_setprio 0
	s_cbranch_vccz .Lwi_sk5
	s_mov_b32 m0, s35
	s_nop 0
	global_load_lds_dwordx4 v232, s[28:29]
	s_add_u32 m0, s35, 0x2000
	s_nop 0
	global_load_lds_dwordx4 v233, s[28:29]
	s_add_u32 m0, s35, 0x4000
	s_nop 0
	global_load_lds_dwordx4 v234, s[28:29]
	s_add_u32 m0, s35, 0x6000
	s_nop 0
	global_load_lds_dwordx4 v235, s[28:29]
.Lwi_sk5:
	ds_read_b128 v[164:167], v207 offset:6144
	ds_read_b128 v[128:131], v209 offset:1024
	ds_read_b128 v[132:135], v209 offset:3072
	ds_read_b128 v[136:139], v209 offset:5120
	ds_read_b128 v[140:143], v209 offset:7168
	s_waitcnt lgkmcnt(6)
	s_setprio 1
	v_mfma_f32_16x16x32_bf16 v[108:111], v[168:171], v[212:215], v[108:111]
	v_mfma_f32_16x16x32_bf16 v[104:107], v[168:171], v[216:219], v[104:107]
	v_mfma_f32_16x16x32_bf16 v[100:103], v[168:171], v[220:223], v[100:103]
	v_mfma_f32_16x16x32_bf16 v[96:99], v[168:171], v[224:227], v[96:99]
	s_setprio 0
	s_cbranch_vccz .Lwi_sk6
	s_add_u32 m0, s35, 0x8000
	s_nop 0
	global_load_lds_dwordx4 v232, s[26:27]
	s_add_u32 m0, s35, 0xa000
	s_nop 0
	global_load_lds_dwordx4 v233, s[26:27]
	s_add_u32 m0, s35, 0xc000
	s_nop 0
	global_load_lds_dwordx4 v234, s[26:27]
	s_add_u32 m0, s35, 0xe000
	s_nop 0
	global_load_lds_dwordx4 v235, s[26:27]
; __device__ __forceinline__ float rsq_(float x) { return __builtin_amdgcn_rsqf(x); }
; #define WAIT_V(n) asm volatile("s_waitcnt vmcnt(%0)" ::"n"(n) : "memory")
; template <int EPI>
; __device__ __forceinline__ void gemm_phase(const Params& p, const u16* __restrict__ A, const u16* __restrict__ Bt, int K, int nN,
;                            u16* __restrict__ Cout, int ldc) {
;     ...
;       GSTEP(0, 2); GSTEP(1, 6); GSTEP(2, 6); GSTEP(3, 6); GSTEP(4, 2); GSTEP(5, 2); GSTEP(6, 2); GSTEP(7, 2);
;       GSTEP(8, 2); GSTEP(9, 2); GSTEP(10, 2); GSTEP(11, 2); GSTEP(12, 2); GSTEP(13, 2); GSTEP(14, 1); GSTEP(15, 0);
;       WAIT_V(0);
;       if (EPI != EPI_SS && t == 0 && tid < 256) rsl[tid] = rsq_(ssv * (1.f / DM) + EPS);
;       __syncthreads();
;     }
.Lwi_sk6:
	ds_read_b128 v[168:171], v207 offset:8192
	s_waitcnt lgkmcnt(6)
	s_setprio 1
	v_mfma_f32_16x16x32_bf16 v[92:95], v[160:163], v[212:215], v[92:95]
	v_mfma_f32_16x16x32_bf16 v[88:91], v[160:163], v[216:219], v[88:91]
	v_mfma_f32_16x16x32_bf16 v[84:87], v[160:163], v[220:223], v[84:87]
	v_mfma_f32_16x16x32_bf16 v[80:83], v[160:163], v[224:227], v[80:83]
	s_setprio 0
	ds_read_b128 v[160:163], v207 offset:10240
	s_waitcnt lgkmcnt(6)
	s_setprio 1
	v_mfma_f32_16x16x32_bf16 v[76:79], v[164:167], v[212:215], v[76:79]
	v_mfma_f32_16x16x32_bf16 v[72:75], v[164:167], v[216:219], v[72:75]
	v_mfma_f32_16x16x32_bf16 v[68:71], v[164:167], v[220:223], v[68:71]
	v_mfma_f32_16x16x32_bf16 v[64:67], v[164:167], v[224:227], v[64:67]
	s_setprio 0
	ds_read_b128 v[164:167], v207 offset:12288
	s_waitcnt lgkmcnt(2)
	s_setprio 1
	v_mfma_f32_16x16x32_bf16 v[60:63], v[168:171], v[212:215], v[60:63]
	v_mfma_f32_16x16x32_bf16 v[56:59], v[168:171], v[216:219], v[56:59]
	v_mfma_f32_16x16x32_bf16 v[52:55], v[168:171], v[220:223], v[52:55]
	v_mfma_f32_16x16x32_bf16 v[48:51], v[168:171], v[224:227], v[48:51]
	s_setprio 0
	ds_read_b128 v[168:171], v207 offset:14336
	s_waitcnt lgkmcnt(2)
	s_setprio 1
	v_mfma_f32_16x16x32_bf16 v[44:47], v[160:163], v[212:215], v[44:47]
	v_mfma_f32_16x16x32_bf16 v[40:43], v[160:163], v[216:219], v[40:43]
	v_mfma_f32_16x16x32_bf16 v[36:39], v[160:163], v[220:223], v[36:39]
	v_mfma_f32_16x16x32_bf16 v[32:35], v[160:163], v[224:227], v[32:35]
	s_setprio 0
	ds_read_b128 v[160:163], v207 offset:1024
	s_waitcnt lgkmcnt(2)
	s_setprio 1
	v_mfma_f32_16x16x32_bf16 v[28:31], v[164:167], v[212:215], v[28:31]
	v_mfma_f32_16x16x32_bf16 v[24:27], v[164:167], v[216:219], v[24:27]
	v_mfma_f32_16x16x32_bf16 v[20:23], v[164:167], v[220:223], v[20:23]
	v_mfma_f32_16x16x32_bf16 v[16:19], v[164:167], v[224:227], v[16:19]
	s_setprio 0
	ds_read_b128 v[164:167], v207 offset:3072
	s_waitcnt lgkmcnt(2)
	s_setprio 1
	v_mfma_f32_16x16x32_bf16 v[12:15], v[168:171], v[212:215], v[12:15]
	v_mfma_f32_16x16x32_bf16 v[8:11], v[168:171], v[216:219], v[8:11]
	v_mfma_f32_16x16x32_bf16 v[4:7], v[168:171], v[220:223], v[4:7]
	v_mfma_f32_16x16x32_bf16 v[0:3], v[168:171], v[224:227], v[0:3]
	s_setprio 0
	ds_read_b128 v[144:147], v207 offset:5120
	s_waitcnt lgkmcnt(2)
	s_setprio 1
	v_mfma_f32_16x16x32_bf16 v[124:127], v[160:163], v[128:131], v[124:127]
	v_mfma_f32_16x16x32_bf16 v[120:123], v[160:163], v[132:135], v[120:123]
	v_mfma_f32_16x16x32_bf16 v[116:119], v[160:163], v[136:139], v[116:119]
	v_mfma_f32_16x16x32_bf16 v[112:115], v[160:163], v[140:143], v[112:115]
	s_setprio 0
	ds_read_b128 v[148:151], v207 offset:7168
	s_waitcnt lgkmcnt(2)
	s_setprio 1
	v_mfma_f32_16x16x32_bf16 v[108:111], v[164:167], v[128:131], v[108:111]
	v_mfma_f32_16x16x32_bf16 v[104:107], v[164:167], v[132:135], v[104:107]
	v_mfma_f32_16x16x32_bf16 v[100:103], v[164:167], v[136:139], v[100:103]
	v_mfma_f32_16x16x32_bf16 v[96:99], v[164:167], v[140:143], v[96:99]
	s_setprio 0
	ds_read_b128 v[152:155], v207 offset:9216
	s_waitcnt lgkmcnt(2)
	s_setprio 1
	v_mfma_f32_16x16x32_bf16 v[92:95], v[144:147], v[128:131], v[92:95]
	v_mfma_f32_16x16x32_bf16 v[88:91], v[144:147], v[132:135], v[88:91]
	v_mfma_f32_16x16x32_bf16 v[84:87], v[144:147], v[136:139], v[84:87]
	v_mfma_f32_16x16x32_bf16 v[80:83], v[144:147], v[140:143], v[80:83]
	s_setprio 0
	ds_read_b128 v[144:147], v207 offset:11264
	s_waitcnt lgkmcnt(2)
	s_setprio 1
	v_mfma_f32_16x16x32_bf16 v[76:79], v[148:151], v[128:131], v[76:79]
	v_mfma_f32_16x16x32_bf16 v[72:75], v[148:151], v[132:135], v[72:75]
	v_mfma_f32_16x16x32_bf16 v[68:71], v[148:151], v[136:139], v[68:71]
	v_mfma_f32_16x16x32_bf16 v[64:67], v[148:151], v[140:143], v[64:67]
	s_setprio 0
	ds_read_b128 v[148:151], v207 offset:13312
	s_waitcnt lgkmcnt(2)
	s_setprio 1
	v_mfma_f32_16x16x32_bf16 v[60:63], v[152:155], v[128:131], v[60:63]
	v_mfma_f32_16x16x32_bf16 v[56:59], v[152:155], v[132:135], v[56:59]
	v_mfma_f32_16x16x32_bf16 v[52:55], v[152:155], v[136:139], v[52:55]
	v_mfma_f32_16x16x32_bf16 v[48:51], v[152:155], v[140:143], v[48:51]
	s_setprio 0
	ds_read_b128 v[152:155], v207 offset:15360
	s_waitcnt lgkmcnt(2)
	s_setprio 1
	v_mfma_f32_16x16x32_bf16 v[44:47], v[144:147], v[128:131], v[44:47]
	v_mfma_f32_16x16x32_bf16 v[40:43], v[144:147], v[132:135], v[40:43]
	v_mfma_f32_16x16x32_bf16 v[36:39], v[144:147], v[136:139], v[36:39]
	v_mfma_f32_16x16x32_bf16 v[32:35], v[144:147], v[140:143], v[32:35]
	s_setprio 0
	s_waitcnt vmcnt(0) lgkmcnt(0)
	s_barrier
	v_xor_b32_e32 v209, 0x10000, v209
	v_xor_b32_e32 v207, 0x10000, v207
	ds_read_b128 v[212:215], v209 offset:0
	ds_read_b128 v[216:219], v209 offset:2048
	ds_read_b128 v[220:223], v209 offset:4096
	ds_read_b128 v[224:227], v209 offset:6144
	ds_read_b128 v[228:231], v207 offset:0
	ds_read_b128 v[168:171], v207 offset:2048
	ds_read_b128 v[160:163], v207 offset:4096
	s_add_u32 s30, s30, 0x80
	s_addc_u32 s31, s31, 0
	s_add_u32 s17, s17, 0x80
	s_addc_u32 s19, s19, 0
	s_xor_b32 s35, s35, 0x10000
	s_add_i32 s34, s34, 1
	s_cmp_lg_u32 s34, -1
	s_cselect_b32 s28, s30, s22
	s_cselect_b32 s29, s31, s23
	s_cselect_b32 s26, s17, s24
	s_cselect_b32 s27, s19, s25
	s_cselect_b64 vcc, -1, s[20:21]
	s_cmp_eq_u32 s34, 0
	s_cselect_b64 vcc, 0, vcc
	s_setprio 1
	v_mfma_f32_16x16x32_bf16 v[28:31], v[148:151], v[128:131], v[28:31]
	v_mfma_f32_16x16x32_bf16 v[24:27], v[148:151], v[132:135], v[24:27]
	v_mfma_f32_16x16x32_bf16 v[20:23], v[148:151], v[136:139], v[20:23]
	v_mfma_f32_16x16x32_bf16 v[16:19], v[148:151], v[140:143], v[16:19]
	s_setprio 0
	s_setprio 1
	v_mfma_f32_16x16x32_bf16 v[12:15], v[152:155], v[128:131], v[12:15]
	v_mfma_f32_16x16x32_bf16 v[8:11], v[152:155], v[132:135], v[8:11]
	v_mfma_f32_16x16x32_bf16 v[4:7], v[152:155], v[136:139], v[4:7]
	v_mfma_f32_16x16x32_bf16 v[0:3], v[152:155], v[140:143], v[0:3]
	s_setprio 0
	s_cmp_lg_u32 s34, 0
	s_cbranch_scc1 .Lwi_head
	s_waitcnt lgkmcnt(0)
	s_branch .LBB0_854

; template <int EPI>
; __device__ __forceinline__ void gemm_phase(const Params& p, const u16* __restrict__ A, const u16* __restrict__ Bt, int K, int nN,
;                            u16* __restrict__ Cout, int ldc) {
;     ...
;       GSTEP(0, 2); GSTEP(1, 6); GSTEP(2, 6); GSTEP(3, 6); GSTEP(4, 2); GSTEP(5, 2); GSTEP(6, 2); GSTEP(7, 2);
;       GSTEP(8, 2); GSTEP(9, 2); GSTEP(10, 2); GSTEP(11, 2); GSTEP(12, 2); GSTEP(13, 2); GSTEP(14, 1); GSTEP(15, 0);
.Lss_head:
	s_waitcnt lgkmcnt(2)
	s_setprio 1
	v_mfma_f32_16x16x32_bf16 v[124:127], v[228:231], v[212:215], v[124:127]
	v_mfma_f32_16x16x32_bf16 v[120:123], v[228:231], v[216:219], v[120:123]
	v_mfma_f32_16x16x32_bf16 v[116:119], v[228:231], v[220:223], v[116:119]
	v_mfma_f32_16x16x32_bf16 v[112:115], v[228:231], v[224:227], v[112:115]
	s_setprio 0
	s_cbranch_vccz .Lss_sk1
	s_mov_b32 m0, s29
	s_nop 0
	global_load_lds_dwordx4 v232, s[34:35]
	s_add_u32 m0, s29, 0x2000
	s_nop 0
	global_load_lds_dwordx4 v233, s[34:35]
	s_add_u32 m0, s29, 0x4000
	s_nop 0
	global_load_lds_dwordx4 v234, s[34:35]
	s_add_u32 m0, s29, 0x6000
	s_nop 0
	global_load_lds_dwordx4 v235, s[34:35]
.Lss_sk1:
	ds_read_b128 v[164:167], v197 offset:6144
	ds_read_b128 v[128:131], v198 offset:1024
	ds_read_b128 v[132:135], v198 offset:3072
	ds_read_b128 v[136:139], v198 offset:5120
	ds_read_b128 v[140:143], v198 offset:7168
	s_waitcnt lgkmcnt(6)
	s_setprio 1
	v_mfma_f32_16x16x32_bf16 v[108:111], v[168:171], v[212:215], v[108:111]
	v_mfma_f32_16x16x32_bf16 v[104:107], v[168:171], v[216:219], v[104:107]
	v_mfma_f32_16x16x32_bf16 v[100:103], v[168:171], v[220:223], v[100:103]
	v_mfma_f32_16x16x32_bf16 v[96:99], v[168:171], v[224:227], v[96:99]
	s_setprio 0
	s_cbranch_vccz .Lss_sk2
	s_add_u32 m0, s29, 0x8000
	s_nop 0
	global_load_lds_dwordx4 v232, s[0:1]
	s_add_u32 m0, s29, 0xa000
	s_nop 0
	global_load_lds_dwordx4 v233, s[0:1]
	s_add_u32 m0, s29, 0xc000
	s_nop 0
	global_load_lds_dwordx4 v234, s[0:1]
	s_add_u32 m0, s29, 0xe000
	s_nop 0
	global_load_lds_dwordx4 v235, s[0:1]
; __device__ __forceinline__ float rsq_(float x) { return __builtin_amdgcn_rsqf(x); }
; #define WAIT_V(n) asm volatile("s_waitcnt vmcnt(%0)" ::"n"(n) : "memory")
; template <int EPI>
; __device__ __forceinline__ void gemm_phase(const Params& p, const u16* __restrict__ A, const u16* __restrict__ Bt, int K, int nN,
;                            u16* __restrict__ Cout, int ldc) {
;     ...
;       GSTEP(0, 2); GSTEP(1, 6); GSTEP(2, 6); GSTEP(3, 6); GSTEP(4, 2); GSTEP(5, 2); GSTEP(6, 2); GSTEP(7, 2);
;       GSTEP(8, 2); GSTEP(9, 2); GSTEP(10, 2); GSTEP(11, 2); GSTEP(12, 2); GSTEP(13, 2); GSTEP(14, 1); GSTEP(15, 0);
;       WAIT_V(0);
;       if (EPI != EPI_SS && t == 0 && tid < 256) rsl[tid] = rsq_(ssv * (1.f / DM) + EPS);
;       __syncthreads();
;     }
.Lss_sk2:
	ds_read_b128 v[168:171], v197 offset:8192
	s_waitcnt lgkmcnt(6)
	s_setprio 1
	v_mfma_f32_16x16x32_bf16 v[92:95], v[160:163], v[212:215], v[92:95]
	v_mfma_f32_16x16x32_bf16 v[88:91], v[160:163], v[216:219], v[88:91]
	v_mfma_f32_16x16x32_bf16 v[84:87], v[160:163], v[220:223], v[84:87]
	v_mfma_f32_16x16x32_bf16 v[80:83], v[160:163], v[224:227], v[80:83]
	s_setprio 0
	ds_read_b128 v[160:163], v197 offset:10240
	s_waitcnt lgkmcnt(6)
	s_setprio 1
	v_mfma_f32_16x16x32_bf16 v[76:79], v[164:167], v[212:215], v[76:79]
	v_mfma_f32_16x16x32_bf16 v[72:75], v[164:167], v[216:219], v[72:75]
	v_mfma_f32_16x16x32_bf16 v[68:71], v[164:167], v[220:223], v[68:71]
	v_mfma_f32_16x16x32_bf16 v[64:67], v[164:167], v[224:227], v[64:67]
	s_setprio 0
	ds_read_b128 v[164:167], v197 offset:12288
	s_waitcnt lgkmcnt(2)
	s_setprio 1
	v_mfma_f32_16x16x32_bf16 v[60:63], v[168:171], v[212:215], v[60:63]
	v_mfma_f32_16x16x32_bf16 v[56:59], v[168:171], v[216:219], v[56:59]
	v_mfma_f32_16x16x32_bf16 v[52:55], v[168:171], v[220:223], v[52:55]
	v_mfma_f32_16x16x32_bf16 v[48:51], v[168:171], v[224:227], v[48:51]
	s_setprio 0
	ds_read_b128 v[168:171], v197 offset:14336
	s_waitcnt lgkmcnt(2)
	s_setprio 1
	v_mfma_f32_16x16x32_bf16 v[44:47], v[160:163], v[212:215], v[44:47]
	v_mfma_f32_16x16x32_bf16 v[40:43], v[160:163], v[216:219], v[40:43]
	v_mfma_f32_16x16x32_bf16 v[36:39], v[160:163], v[220:223], v[36:39]
	v_mfma_f32_16x16x32_bf16 v[32:35], v[160:163], v[224:227], v[32:35]
	s_setprio 0
	ds_read_b128 v[160:163], v197 offset:1024
	s_waitcnt lgkmcnt(2)
	s_setprio 1
	v_mfma_f32_16x16x32_bf16 v[28:31], v[164:167], v[212:215], v[28:31]
	v_mfma_f32_16x16x32_bf16 v[24:27], v[164:167], v[216:219], v[24:27]
	v_mfma_f32_16x16x32_bf16 v[20:23], v[164:167], v[220:223], v[20:23]
	v_mfma_f32_16x16x32_bf16 v[16:19], v[164:167], v[224:227], v[16:19]
	s_setprio 0
	ds_read_b128 v[164:167], v197 offset:3072
	s_waitcnt lgkmcnt(2)
	s_setprio 1
	v_mfma_f32_16x16x32_bf16 v[12:15], v[168:171], v[212:215], v[12:15]
	v_mfma_f32_16x16x32_bf16 v[8:11], v[168:171], v[216:219], v[8:11]
	v_mfma_f32_16x16x32_bf16 v[4:7], v[168:171], v[220:223], v[4:7]
	v_mfma_f32_16x16x32_bf16 v[0:3], v[168:171], v[224:227], v[0:3]
	s_setprio 0
	ds_read_b128 v[144:147], v197 offset:5120
	s_waitcnt lgkmcnt(2)
	s_setprio 1
	v_mfma_f32_16x16x32_bf16 v[124:127], v[160:163], v[128:131], v[124:127]
	v_mfma_f32_16x16x32_bf16 v[120:123], v[160:163], v[132:135], v[120:123]
	v_mfma_f32_16x16x32_bf16 v[116:119], v[160:163], v[136:139], v[116:119]
	v_mfma_f32_16x16x32_bf16 v[112:115], v[160:163], v[140:143], v[112:115]
	s_setprio 0
	ds_read_b128 v[148:151], v197 offset:7168
	s_waitcnt lgkmcnt(2)
	s_setprio 1
	v_mfma_f32_16x16x32_bf16 v[108:111], v[164:167], v[128:131], v[108:111]
	v_mfma_f32_16x16x32_bf16 v[104:107], v[164:167], v[132:135], v[104:107]
	v_mfma_f32_16x16x32_bf16 v[100:103], v[164:167], v[136:139], v[100:103]
	v_mfma_f32_16x16x32_bf16 v[96:99], v[164:167], v[140:143], v[96:99]
	s_setprio 0
	ds_read_b128 v[152:155], v197 offset:9216
	s_waitcnt lgkmcnt(2)
	s_setprio 1
	v_mfma_f32_16x16x32_bf16 v[92:95], v[144:147], v[128:131], v[92:95]
	v_mfma_f32_16x16x32_bf16 v[88:91], v[144:147], v[132:135], v[88:91]
	v_mfma_f32_16x16x32_bf16 v[84:87], v[144:147], v[136:139], v[84:87]
	v_mfma_f32_16x16x32_bf16 v[80:83], v[144:147], v[140:143], v[80:83]
	s_setprio 0
	ds_read_b128 v[144:147], v197 offset:11264
	s_waitcnt lgkmcnt(2)
	s_setprio 1
	v_mfma_f32_16x16x32_bf16 v[76:79], v[148:151], v[128:131], v[76:79]
	v_mfma_f32_16x16x32_bf16 v[72:75], v[148:151], v[132:135], v[72:75]
	v_mfma_f32_16x16x32_bf16 v[68:71], v[148:151], v[136:139], v[68:71]
	v_mfma_f32_16x16x32_bf16 v[64:67], v[148:151], v[140:143], v[64:67]
	s_setprio 0
	ds_read_b128 v[148:151], v197 offset:13312
	s_waitcnt lgkmcnt(2)
	s_setprio 1
	v_mfma_f32_16x16x32_bf16 v[60:63], v[152:155], v[128:131], v[60:63]
	v_mfma_f32_16x16x32_bf16 v[56:59], v[152:155], v[132:135], v[56:59]
	v_mfma_f32_16x16x32_bf16 v[52:55], v[152:155], v[136:139], v[52:55]
	v_mfma_f32_16x16x32_bf16 v[48:51], v[152:155], v[140:143], v[48:51]
	s_setprio 0
	ds_read_b128 v[152:155], v197 offset:15360
	s_waitcnt lgkmcnt(2)
	s_setprio 1
	v_mfma_f32_16x16x32_bf16 v[44:47], v[144:147], v[128:131], v[44:47]
	v_mfma_f32_16x16x32_bf16 v[40:43], v[144:147], v[132:135], v[40:43]
	v_mfma_f32_16x16x32_bf16 v[36:39], v[144:147], v[136:139], v[36:39]
	v_mfma_f32_16x16x32_bf16 v[32:35], v[144:147], v[140:143], v[32:35]
	s_setprio 0
	s_waitcnt vmcnt(0) lgkmcnt(0)
	s_barrier
	v_xor_b32_e32 v198, 0x10000, v198
	v_xor_b32_e32 v197, 0x10000, v197
	ds_read_b128 v[212:215], v198 offset:0
	ds_read_b128 v[216:219], v198 offset:2048
	ds_read_b128 v[220:223], v198 offset:4096
	ds_read_b128 v[224:227], v198 offset:6144
	ds_read_b128 v[228:231], v197 offset:0
	ds_read_b128 v[168:171], v197 offset:2048
	ds_read_b128 v[160:163], v197 offset:4096
	s_add_u32 s34, s34, 0x80
	s_addc_u32 s35, s35, 0
	s_add_u32 s0, s0, 0x80
	s_addc_u32 s1, s1, 0
	s_xor_b32 s29, s29, 0x10000
	s_add_i32 s30, s30, 1
	s_cmp_lg_u32 s30, -1
	s_cselect_b32 s34, s34, s10
	s_cselect_b32 s35, s35, s11
	s_cselect_b32 s0, s0, s6
	s_cselect_b32 s1, s1, s7
	s_cselect_b64 vcc, -1, s[12:13]
	s_cmp_eq_u32 s30, 0
	s_cselect_b64 vcc, 0, vcc
	s_setprio 1
	v_mfma_f32_16x16x32_bf16 v[28:31], v[148:151], v[128:131], v[28:31]
	v_mfma_f32_16x16x32_bf16 v[24:27], v[148:151], v[132:135], v[24:27]
	v_mfma_f32_16x16x32_bf16 v[20:23], v[148:151], v[136:139], v[20:23]
	v_mfma_f32_16x16x32_bf16 v[16:19], v[148:151], v[140:143], v[16:19]
	s_setprio 0
	s_setprio 1
	v_mfma_f32_16x16x32_bf16 v[12:15], v[152:155], v[128:131], v[12:15]
	v_mfma_f32_16x16x32_bf16 v[8:11], v[152:155], v[132:135], v[8:11]
	v_mfma_f32_16x16x32_bf16 v[4:7], v[152:155], v[136:139], v[4:7]
	v_mfma_f32_16x16x32_bf16 v[0:3], v[152:155], v[140:143], v[0:3]
	s_setprio 0
	s_cmp_lg_u32 s30, 0
	s_cbranch_scc1 .Lss_head
	s_waitcnt lgkmcnt(0)
	v_mov_b32_e32 v128, v124
	v_mov_b32_e32 v129, v125
	v_mov_b32_e32 v130, v126
	v_mov_b32_e32 v131, v127
	v_mov_b32_e32 v132, v120
	v_mov_b32_e32 v133, v121
	v_mov_b32_e32 v134, v122
	v_mov_b32_e32 v135, v123
	v_mov_b32_e32 v136, v116
	v_mov_b32_e32 v137, v117
	v_mov_b32_e32 v138, v118
	v_mov_b32_e32 v139, v119
	v_mov_b32_e32 v140, v112
	v_mov_b32_e32 v141, v113
	v_mov_b32_e32 v142, v114
	v_mov_b32_e32 v143, v115
	v_mov_b32_e32 v148, v64
	v_mov_b32_e32 v149, v65
	v_mov_b32_e32 v150, v66
	v_mov_b32_e32 v151, v67
	s_branch .Lss_epi

; template <int EPI>
; __device__ __forceinline__ void gemm_phase(const Params& p, const u16* __restrict__ A, const u16* __restrict__ Bt, int K, int nN,
;                            u16* __restrict__ Cout, int ldc) {
;     ...
;       GSTEP(0, 2); GSTEP(1, 6); GSTEP(2, 6); GSTEP(3, 6); GSTEP(4, 2); GSTEP(5, 2); GSTEP(6, 2); GSTEP(7, 2);
;       GSTEP(8, 2); GSTEP(9, 2); GSTEP(10, 2); GSTEP(11, 2); GSTEP(12, 2); GSTEP(13, 2); GSTEP(14, 1); GSTEP(15, 0);
.Lgu_head:
	s_waitcnt lgkmcnt(2)
	s_setprio 1
	v_mfma_f32_16x16x32_bf16 v[124:127], v[228:231], v[212:215], v[124:127]
	v_mfma_f32_16x16x32_bf16 v[120:123], v[228:231], v[216:219], v[120:123]
	v_mfma_f32_16x16x32_bf16 v[116:119], v[228:231], v[220:223], v[116:119]
	v_mfma_f32_16x16x32_bf16 v[112:115], v[228:231], v[224:227], v[112:115]
	s_setprio 0
	s_cbranch_vccz .Lgu_sk3
	s_mov_b32 m0, s40
	s_nop 0
	global_load_lds_dwordx4 v232, s[22:23]
	s_add_u32 m0, s40, 0x2000
	s_nop 0
	global_load_lds_dwordx4 v233, s[22:23]
	s_add_u32 m0, s40, 0x4000
	s_nop 0
	global_load_lds_dwordx4 v234, s[22:23]
	s_add_u32 m0, s40, 0x6000
	s_nop 0
	global_load_lds_dwordx4 v235, s[22:23]
.Lgu_sk3:
	ds_read_b128 v[164:167], v206 offset:6144
	ds_read_b128 v[128:131], v208 offset:1024
	ds_read_b128 v[132:135], v208 offset:3072
	ds_read_b128 v[136:139], v208 offset:5120
	ds_read_b128 v[140:143], v208 offset:7168
	s_waitcnt lgkmcnt(6)
	s_setprio 1
	v_mfma_f32_16x16x32_bf16 v[108:111], v[168:171], v[212:215], v[108:111]
	v_mfma_f32_16x16x32_bf16 v[104:107], v[168:171], v[216:219], v[104:107]
	v_mfma_f32_16x16x32_bf16 v[100:103], v[168:171], v[220:223], v[100:103]
	v_mfma_f32_16x16x32_bf16 v[96:99], v[168:171], v[224:227], v[96:99]
	s_setprio 0
	s_cbranch_vccz .Lgu_sk4
	s_add_u32 m0, s40, 0x8000
	s_nop 0
	global_load_lds_dwordx4 v232, s[20:21]
	s_add_u32 m0, s40, 0xa000
	s_nop 0
	global_load_lds_dwordx4 v233, s[20:21]
	s_add_u32 m0, s40, 0xc000
	s_nop 0
	global_load_lds_dwordx4 v234, s[20:21]
	s_add_u32 m0, s40, 0xe000
	s_nop 0
	global_load_lds_dwordx4 v235, s[20:21]
; __device__ __forceinline__ float rsq_(float x) { return __builtin_amdgcn_rsqf(x); }
; #define WAIT_V(n) asm volatile("s_waitcnt vmcnt(%0)" ::"n"(n) : "memory")
; template <int EPI>
; __device__ __forceinline__ void gemm_phase(const Params& p, const u16* __restrict__ A, const u16* __restrict__ Bt, int K, int nN,
;                            u16* __restrict__ Cout, int ldc) {
;     ...
;       GSTEP(0, 2); GSTEP(1, 6); GSTEP(2, 6); GSTEP(3, 6); GSTEP(4, 2); GSTEP(5, 2); GSTEP(6, 2); GSTEP(7, 2);
;       GSTEP(8, 2); GSTEP(9, 2); GSTEP(10, 2); GSTEP(11, 2); GSTEP(12, 2); GSTEP(13, 2); GSTEP(14, 1); GSTEP(15, 0);
;       WAIT_V(0);
;       if (EPI != EPI_SS && t == 0 && tid < 256) rsl[tid] = rsq_(ssv * (1.f / DM) + EPS);
;       __syncthreads();
;     }
.Lgu_sk4:
	ds_read_b128 v[168:171], v206 offset:8192
	s_waitcnt lgkmcnt(6)
	s_setprio 1
	v_mfma_f32_16x16x32_bf16 v[92:95], v[160:163], v[212:215], v[92:95]
	v_mfma_f32_16x16x32_bf16 v[88:91], v[160:163], v[216:219], v[88:91]
	v_mfma_f32_16x16x32_bf16 v[84:87], v[160:163], v[220:223], v[84:87]
	v_mfma_f32_16x16x32_bf16 v[80:83], v[160:163], v[224:227], v[80:83]
	s_setprio 0
	ds_read_b128 v[160:163], v206 offset:10240
	s_waitcnt lgkmcnt(6)
	s_setprio 1
	v_mfma_f32_16x16x32_bf16 v[76:79], v[164:167], v[212:215], v[76:79]
	v_mfma_f32_16x16x32_bf16 v[72:75], v[164:167], v[216:219], v[72:75]
	v_mfma_f32_16x16x32_bf16 v[68:71], v[164:167], v[220:223], v[68:71]
	v_mfma_f32_16x16x32_bf16 v[64:67], v[164:167], v[224:227], v[64:67]
	s_setprio 0
	ds_read_b128 v[164:167], v206 offset:12288
	s_waitcnt lgkmcnt(2)
	s_setprio 1
	v_mfma_f32_16x16x32_bf16 v[60:63], v[168:171], v[212:215], v[60:63]
	v_mfma_f32_16x16x32_bf16 v[56:59], v[168:171], v[216:219], v[56:59]
	v_mfma_f32_16x16x32_bf16 v[52:55], v[168:171], v[220:223], v[52:55]
	v_mfma_f32_16x16x32_bf16 v[48:51], v[168:171], v[224:227], v[48:51]
	s_setprio 0
	ds_read_b128 v[168:171], v206 offset:14336
	s_waitcnt lgkmcnt(2)
	s_setprio 1
	v_mfma_f32_16x16x32_bf16 v[44:47], v[160:163], v[212:215], v[44:47]
	v_mfma_f32_16x16x32_bf16 v[40:43], v[160:163], v[216:219], v[40:43]
	v_mfma_f32_16x16x32_bf16 v[36:39], v[160:163], v[220:223], v[36:39]
	v_mfma_f32_16x16x32_bf16 v[32:35], v[160:163], v[224:227], v[32:35]
	s_setprio 0
	ds_read_b128 v[160:163], v206 offset:1024
	s_waitcnt lgkmcnt(2)
	s_setprio 1
	v_mfma_f32_16x16x32_bf16 v[28:31], v[164:167], v[212:215], v[28:31]
	v_mfma_f32_16x16x32_bf16 v[24:27], v[164:167], v[216:219], v[24:27]
	v_mfma_f32_16x16x32_bf16 v[20:23], v[164:167], v[220:223], v[20:23]
	v_mfma_f32_16x16x32_bf16 v[16:19], v[164:167], v[224:227], v[16:19]
	s_setprio 0
	ds_read_b128 v[164:167], v206 offset:3072
	s_waitcnt lgkmcnt(2)
	s_setprio 1
	v_mfma_f32_16x16x32_bf16 v[12:15], v[168:171], v[212:215], v[12:15]
	v_mfma_f32_16x16x32_bf16 v[8:11], v[168:171], v[216:219], v[8:11]
	v_mfma_f32_16x16x32_bf16 v[4:7], v[168:171], v[220:223], v[4:7]
	v_mfma_f32_16x16x32_bf16 v[0:3], v[168:171], v[224:227], v[0:3]
	s_setprio 0
	ds_read_b128 v[144:147], v206 offset:5120
	s_waitcnt lgkmcnt(2)
	s_setprio 1
	v_mfma_f32_16x16x32_bf16 v[124:127], v[160:163], v[128:131], v[124:127]
	v_mfma_f32_16x16x32_bf16 v[120:123], v[160:163], v[132:135], v[120:123]
	v_mfma_f32_16x16x32_bf16 v[116:119], v[160:163], v[136:139], v[116:119]
	v_mfma_f32_16x16x32_bf16 v[112:115], v[160:163], v[140:143], v[112:115]
	s_setprio 0
	ds_read_b128 v[148:151], v206 offset:7168
	s_waitcnt lgkmcnt(2)
	s_setprio 1
	v_mfma_f32_16x16x32_bf16 v[108:111], v[164:167], v[128:131], v[108:111]
	v_mfma_f32_16x16x32_bf16 v[104:107], v[164:167], v[132:135], v[104:107]
	v_mfma_f32_16x16x32_bf16 v[100:103], v[164:167], v[136:139], v[100:103]
	v_mfma_f32_16x16x32_bf16 v[96:99], v[164:167], v[140:143], v[96:99]
	s_setprio 0
	ds_read_b128 v[152:155], v206 offset:9216
	s_waitcnt lgkmcnt(2)
	s_setprio 1
	v_mfma_f32_16x16x32_bf16 v[92:95], v[144:147], v[128:131], v[92:95]
	v_mfma_f32_16x16x32_bf16 v[88:91], v[144:147], v[132:135], v[88:91]
	v_mfma_f32_16x16x32_bf16 v[84:87], v[144:147], v[136:139], v[84:87]
	v_mfma_f32_16x16x32_bf16 v[80:83], v[144:147], v[140:143], v[80:83]
	s_setprio 0
	ds_read_b128 v[144:147], v206 offset:11264
	s_waitcnt lgkmcnt(2)
	s_setprio 1
	v_mfma_f32_16x16x32_bf16 v[76:79], v[148:151], v[128:131], v[76:79]
	v_mfma_f32_16x16x32_bf16 v[72:75], v[148:151], v[132:135], v[72:75]
	v_mfma_f32_16x16x32_bf16 v[68:71], v[148:151], v[136:139], v[68:71]
	v_mfma_f32_16x16x32_bf16 v[64:67], v[148:151], v[140:143], v[64:67]
	s_setprio 0
	ds_read_b128 v[148:151], v206 offset:13312
	s_waitcnt lgkmcnt(2)
	s_setprio 1
	v_mfma_f32_16x16x32_bf16 v[60:63], v[152:155], v[128:131], v[60:63]
	v_mfma_f32_16x16x32_bf16 v[56:59], v[152:155], v[132:135], v[56:59]
	v_mfma_f32_16x16x32_bf16 v[52:55], v[152:155], v[136:139], v[52:55]
	v_mfma_f32_16x16x32_bf16 v[48:51], v[152:155], v[140:143], v[48:51]
	s_setprio 0
	ds_read_b128 v[152:155], v206 offset:15360
	s_waitcnt lgkmcnt(2)
	s_setprio 1
	v_mfma_f32_16x16x32_bf16 v[44:47], v[144:147], v[128:131], v[44:47]
	v_mfma_f32_16x16x32_bf16 v[40:43], v[144:147], v[132:135], v[40:43]
	v_mfma_f32_16x16x32_bf16 v[36:39], v[144:147], v[136:139], v[36:39]
	v_mfma_f32_16x16x32_bf16 v[32:35], v[144:147], v[140:143], v[32:35]
	s_setprio 0
	s_waitcnt vmcnt(0) lgkmcnt(0)
	s_barrier
	v_xor_b32_e32 v208, 0x10000, v208
	v_xor_b32_e32 v206, 0x10000, v206
	ds_read_b128 v[212:215], v208 offset:0
	ds_read_b128 v[216:219], v208 offset:2048
	ds_read_b128 v[220:223], v208 offset:4096
	ds_read_b128 v[224:227], v208 offset:6144
	ds_read_b128 v[228:231], v206 offset:0
	ds_read_b128 v[168:171], v206 offset:2048
	ds_read_b128 v[160:163], v206 offset:4096
	s_add_u32 s25, s25, 0x80
	s_addc_u32 s26, s26, 0
	s_add_u32 s13, s13, 0x80
	s_addc_u32 s24, s24, 0
	s_xor_b32 s40, s40, 0x10000
	s_add_i32 s27, s27, 1
	s_cmp_lg_u32 s27, -1
	s_cselect_b32 s22, s25, s16
	s_cselect_b32 s23, s26, s17
	s_cselect_b32 s20, s13, s18
	s_cselect_b32 s21, s24, s19
	s_cselect_b64 vcc, -1, s[10:11]
	s_cmp_eq_u32 s27, 0
	s_cselect_b64 vcc, 0, vcc
	s_setprio 1
	v_mfma_f32_16x16x32_bf16 v[28:31], v[148:151], v[128:131], v[28:31]
	v_mfma_f32_16x16x32_bf16 v[24:27], v[148:151], v[132:135], v[24:27]
	v_mfma_f32_16x16x32_bf16 v[20:23], v[148:151], v[136:139], v[20:23]
	v_mfma_f32_16x16x32_bf16 v[16:19], v[148:151], v[140:143], v[16:19]
	s_setprio 0
	s_setprio 1
	v_mfma_f32_16x16x32_bf16 v[12:15], v[152:155], v[128:131], v[12:15]
	v_mfma_f32_16x16x32_bf16 v[8:11], v[152:155], v[132:135], v[8:11]
	v_mfma_f32_16x16x32_bf16 v[4:7], v[152:155], v[136:139], v[4:7]
	v_mfma_f32_16x16x32_bf16 v[0:3], v[152:155], v[140:143], v[0:3]
	s_setprio 0
	s_cmp_lg_u32 s27, 0
	s_cbranch_scc1 .Lgu_head
	s_waitcnt lgkmcnt(0)
	s_branch .LBB0_1126
